# phases B, G, I: tile prologue no longer drains the previous tile's stores (vmcnt(0) -> lgkmcnt(0)) before the first LDS-DMA loads
# speedup vs baseline: 1.0051x; 1.0003x over previous
; #define WAIT_V(n) asm volatile("s_waitcnt vmcnt(" #n ")" ::: "memory")
; DI void gemm256(int wv0, f32x4 (&acc)[2][2][4][2], const u16* __restrict__ A, int lda, const u16* __restrict__ Bt, int ldb,
;                 int K, unsigned char* smem) {
;   u16* shm = (u16*)smem;
;   const int tid = my_tid(wv0), lane = tid & 63;
;   const int wr = wv0 >> 2, wc = wv0 & 3, fr = lane & 15, fq = lane >> 4;
;     ...
;   int sr0, sc0, sr1, sc1;
;   stage_rc(tid * 16, sr0, sc0);
;   stage_rc(tid * 16 + 8192, sr1, sc1);
;   const u16* a0 = A + (size_t)sr0 * lda + sc0;
;   const u16* a1 = A + (size_t)sr1 * lda + sc1;
;   const u16* b0 = Bt + (size_t)sr0 * ldb + sc0;
;   const u16* b1 = Bt + (size_t)sr1 * ldb + sc1;
;     ...
;   WAIT_V(0);
;   __syncthreads();
;   STAGE_B(SB(0, 0), 0, 0) STAGE_A(SA(0, 0), 0, 0)
;   STAGE_B(SB(0, 1), 1, 0) STAGE_A(SA(0, 1), 1, 0)
.LBB0_157:
	v_mov_b32_e32 v12, v154
	s_lshr_b32 s4, s94, 4
	v_ashrrev_i32_e32 v0, 31, v12
	v_lshrrev_b32_e32 v0, 26, v0
	v_add_u32_e32 v0, v12, v0
	v_ashrrev_i32_e32 v1, 6, v0
	v_bfe_i32 v0, v12, 27, 1
	v_lshlrev_b32_e32 v13, 4, v12
	v_lshrrev_b32_e32 v0, 22, v0
	v_add_u32_e32 v0, v13, v0
	v_and_b32_e32 v0, 0xfffffc00, v0
	v_sub_u32_e32 v0, v13, v0
	v_lshrrev_b32_e32 v2, 4, v0
	v_bitop3_b32 v2, v2, v0, 32 bitop3:0x6c
	v_ashrrev_i32_e32 v0, 31, v0
	v_lshrrev_b32_e32 v0, 26, v0
	v_lshlrev_b32_e32 v3, 3, v1
	v_add_u32_e32 v0, v2, v0
	v_and_b32_e32 v3, -16, v3
	v_ashrrev_i32_e32 v4, 6, v0
	v_add_u32_e32 v0, v4, v3
	v_mul_i32_i24_e32 v3, 64, v4
	v_lshlrev_b32_e32 v1, 5, v1
	v_sub_u32_e32 v2, v2, v3
	v_and_b32_e32 v1, 32, v1
	v_ashrrev_i16_sdwa v2, v156, sext(v2) dst_sel:DWORD dst_unused:UNUSED_PAD src0_sel:DWORD src1_sel:BYTE_0
	v_add_u32_sdwa v4, v1, sext(v2) dst_sel:DWORD dst_unused:UNUSED_PAD src0_sel:DWORD src1_sel:WORD_0
	v_add_u32_e32 v1, 0x2000, v13
	v_ashrrev_i32_e32 v2, 31, v1
	v_lshrrev_b32_e32 v2, 22, v2
	v_add_u32_e32 v2, v1, v2
	v_ashrrev_i32_e32 v3, 10, v2
	s_and_b32 s7, s4, 0xfffff0
	s_lshl_b32 s4, s94, 1
	v_mul_i32_i24_e32 v2, 0x400, v3
	s_and_b32 s10, s4, 12
	v_sub_u32_e32 v1, v1, v2
	s_or_b32 s4, s7, s10
	s_bfe_u32 s64, s94, 0x20006
	v_lshrrev_b32_e32 v2, 4, v1
	s_or_b32 s62, s4, s64
	s_lshl_b32 s4, s94, 3
	s_bfe_u32 s5, s94, 0x30003
	s_lshr_b32 s6, s94, 8
	v_bitop3_b32 v1, v2, v1, 32 bitop3:0x6c
	s_or_b32 s63, s5, s4
	s_mul_i32 s6, s6, 5
	s_lshl_b32 s62, s62, 8
	v_ashrrev_i32_e32 v5, 31, v1
	s_add_i32 s63, s63, s6
	s_sub_i32 s62, 0x7f00, s62
	v_lshrrev_b32_e32 v5, 26, v5
	s_and_b32 s66, s63, 15
	s_ashr_i32 s63, s62, 31
	v_add_u32_e32 v5, v1, v5
	s_lshl_b64 s[68:69], s[62:63], 11
	v_ashrrev_i32_e32 v6, 6, v5
	v_and_b32_e32 v5, 0xc0, v5
	s_add_u32 s68, s0, s68
	v_lshlrev_b32_e32 v2, 3, v3
	v_lshlrev_b32_e32 v3, 5, v3
	v_sub_u32_e32 v1, v1, v5
	s_addc_u32 s69, s1, s69
	s_lshl_b32 s63, s66, 19
	v_and_b32_e32 v2, -16, v2
	v_and_b32_e32 v3, 32, v3
	v_ashrrev_i16_sdwa v1, v156, sext(v1) dst_sel:DWORD dst_unused:UNUSED_PAD src0_sel:DWORD src1_sel:BYTE_0
	s_add_u32 s70, s12, s63
	v_add_u32_e32 v2, v6, v2
	v_add_u32_sdwa v6, v3, sext(v1) dst_sel:DWORD dst_unused:UNUSED_PAD src0_sel:DWORD src1_sel:WORD_0
	v_ashrrev_i32_e32 v1, 31, v0
	s_addc_u32 s71, s13, 0
	v_ashrrev_i32_e32 v5, 31, v4
	v_ashrrev_i32_e32 v3, 31, v2
	v_lshlrev_b64 v[0:1], 11, v[0:1]
	s_add_i32 s63, 32, 0x10000
	v_ashrrev_i32_e32 v7, 31, v6
	v_lshlrev_b64 v[2:3], 11, v[2:3]
	v_lshl_add_u64 v[10:11], s[68:69], 0, v[0:1]
	v_lshlrev_b64 v[4:5], 1, v[4:5]
	v_add_u32_e32 v147, s63, v13
	v_lshl_add_u64 v[8:9], s[70:71], 0, v[0:1]
	v_lshl_add_u64 v[130:131], v[10:11], 0, v[4:5]
	v_lshl_add_u64 v[10:11], s[68:69], 0, v[2:3]
	v_lshlrev_b64 v[6:7], 1, v[6:7]
	v_readfirstlane_b32 s63, v147
	v_add_u32_e32 v148, 0x2000, v147
	v_lshl_add_u64 v[14:15], s[70:71], 0, v[2:3]
	v_lshl_add_u64 v[128:129], v[10:11], 0, v[6:7]
	v_lshl_add_u64 v[10:11], v[8:9], 0, v[4:5]
	s_mov_b32 m0, s63
	v_readfirstlane_b32 s63, v148
	v_add_u32_e32 v149, 32, v13
	v_lshl_add_u64 v[8:9], v[14:15], 0, v[6:7]
	s_waitcnt lgkmcnt(0)
	s_barrier
	global_load_lds_dwordx4 v[10:11], off
	s_mov_b32 m0, s63
	v_readfirstlane_b32 s63, v149
	v_add_u32_e32 v150, 0x2000, v149
	global_load_lds_dwordx4 v[8:9], off
	s_mov_b32 m0, s63
	v_readfirstlane_b32 s63, v150
	global_load_lds_dwordx4 v[130:131], off
	s_mov_b32 m0, s63
	s_add_i32 s63, 32, 0x14000
	v_add_u32_e32 v151, s63, v13
	v_add_u32_e32 v152, 0x2000, v151
	v_readfirstlane_b32 s63, v151
	global_load_lds_dwordx4 v[128:129], off
	v_lshl_add_u64 v[14:15], v[10:11], 0, s[36:37]
	s_mov_b32 m0, s63
	v_readfirstlane_b32 s63, v152
	v_add_u32_e32 v153, 0x4000, v149
	global_load_lds_dwordx4 v[14:15], off
	v_lshl_add_u64 v[14:15], v[8:9], 0, s[36:37]
	s_mov_b32 m0, s63
	v_readfirstlane_b32 s63, v153
	v_add_u32_e32 v157, 0x6000, v149
	global_load_lds_dwordx4 v[14:15], off
	v_lshl_add_u64 v[14:15], v[130:131], 0, s[36:37]
	s_mov_b32 m0, s63
	v_readfirstlane_b32 s63, v157
	global_load_lds_dwordx4 v[14:15], off
	v_lshl_add_u64 v[14:15], v[128:129], 0, s[36:37]
	s_mov_b32 m0, s63
	s_andn2_b64 vcc, exec, s[14:15]
	global_load_lds_dwordx4 v[14:15], off
	s_cbranch_vccnz .LBB0_159
	s_barrier

; #define WAIT_V(n) asm volatile("s_waitcnt vmcnt(" #n ")" ::: "memory")
; DI void gemm256(int wv0, f32x4 (&acc)[2][2][4][2], const u16* __restrict__ A, int lda, const u16* __restrict__ Bt, int ldb,
;                 int K, unsigned char* smem) {
;   u16* shm = (u16*)smem;
;   const int tid = my_tid(wv0), lane = tid & 63;
;   const int wr = wv0 >> 2, wc = wv0 & 3, fr = lane & 15, fq = lane >> 4;
;     ...
;   int sr0, sc0, sr1, sc1;
;   stage_rc(tid * 16, sr0, sc0);
;   stage_rc(tid * 16 + 8192, sr1, sc1);
;   const u16* a0 = A + (size_t)sr0 * lda + sc0;
;   const u16* a1 = A + (size_t)sr1 * lda + sc1;
;   const u16* b0 = Bt + (size_t)sr0 * ldb + sc0;
;   const u16* b1 = Bt + (size_t)sr1 * ldb + sc1;
;     ...
;   WAIT_V(0);
;   __syncthreads();
;   STAGE_B(SB(0, 0), 0, 0) STAGE_A(SA(0, 0), 0, 0)
;   STAGE_B(SB(0, 1), 1, 0) STAGE_A(SA(0, 1), 1, 0)
.LBB0_1054:
	v_mov_b32_e32 v12, v140
	s_lshr_b32 s8, s67, 2
	v_ashrrev_i32_e32 v0, 31, v12
	v_lshrrev_b32_e32 v0, 26, v0
	v_add_u32_e32 v0, v12, v0
	v_ashrrev_i32_e32 v1, 6, v0
	v_bfe_i32 v0, v12, 27, 1
	v_lshlrev_b32_e32 v13, 4, v12
	v_lshrrev_b32_e32 v0, 22, v0
	v_add_u32_e32 v0, v13, v0
	v_and_b32_e32 v0, 0xfffffc00, v0
	v_sub_u32_e32 v0, v13, v0
	v_lshrrev_b32_e32 v2, 4, v0
	v_bitop3_b32 v2, v2, v0, 32 bitop3:0x6c
	v_ashrrev_i32_e32 v0, 31, v0
	v_lshrrev_b32_e32 v0, 26, v0
	v_lshlrev_b32_e32 v3, 3, v1
	v_add_u32_e32 v0, v2, v0
	v_and_b32_e32 v3, -16, v3
	v_ashrrev_i32_e32 v4, 6, v0
	v_add_u32_e32 v0, v4, v3
	v_mul_i32_i24_e32 v3, 64, v4
	v_lshlrev_b32_e32 v1, 5, v1
	v_sub_u32_e32 v2, v2, v3
	v_and_b32_e32 v1, 32, v1
	v_ashrrev_i16_sdwa v2, v143, sext(v2) dst_sel:DWORD dst_unused:UNUSED_PAD src0_sel:DWORD src1_sel:BYTE_0
	v_add_u32_sdwa v4, v1, sext(v2) dst_sel:DWORD dst_unused:UNUSED_PAD src0_sel:DWORD src1_sel:WORD_0
	v_add_u32_e32 v1, 0x2000, v13
	v_ashrrev_i32_e32 v2, 31, v1
	v_lshrrev_b32_e32 v2, 22, v2
	v_add_u32_e32 v2, v1, v2
	v_ashrrev_i32_e32 v3, 10, v2
	s_and_b32 s48, s8, 0xffffc0
	s_lshl_b32 s8, s67, 3
	v_mul_i32_i24_e32 v2, 0x400, v3
	s_and_b32 s49, s8, 56
	v_sub_u32_e32 v1, v1, v2
	s_or_b32 s8, s48, s49
	s_bfe_u32 s69, s67, 0x30005
	v_lshrrev_b32_e32 v2, 4, v1
	s_or_b32 s8, s8, s69
	v_bitop3_b32 v1, v2, v1, 32 bitop3:0x6c
	s_lshl_b32 s8, s8, 8
	v_ashrrev_i32_e32 v5, 31, v1
	s_sub_i32 s46, 0x7f00, s8
	v_lshrrev_b32_e32 v5, 26, v5
	s_ashr_i32 s47, s46, 31
	v_add_u32_e32 v5, v1, v5
	s_bfe_u32 s68, s67, 0x20003
	s_lshl_b64 s[70:71], s[46:47], 11
	v_ashrrev_i32_e32 v6, 6, v5
	v_and_b32_e32 v5, 0xc0, v5
	s_add_u32 s70, s0, s70
	v_lshlrev_b32_e32 v2, 3, v3
	v_lshlrev_b32_e32 v3, 5, v3
	v_sub_u32_e32 v1, v1, v5
	s_addc_u32 s71, s1, s71
	s_lshl_b32 s8, s68, 19
	v_and_b32_e32 v2, -16, v2
	v_and_b32_e32 v3, 32, v3
	v_ashrrev_i16_sdwa v1, v143, sext(v1) dst_sel:DWORD dst_unused:UNUSED_PAD src0_sel:DWORD src1_sel:BYTE_0
	s_add_u32 s72, s33, s8
	v_add_u32_e32 v2, v6, v2
	v_add_u32_sdwa v6, v3, sext(v1) dst_sel:DWORD dst_unused:UNUSED_PAD src0_sel:DWORD src1_sel:WORD_0
	v_ashrrev_i32_e32 v1, 31, v0
	s_addc_u32 s73, s50, 0
	v_ashrrev_i32_e32 v5, 31, v4
	v_ashrrev_i32_e32 v3, 31, v2
	v_lshlrev_b64 v[0:1], 11, v[0:1]
	s_add_i32 s47, 32, 0x10000
	v_ashrrev_i32_e32 v7, 31, v6
	v_lshlrev_b64 v[2:3], 11, v[2:3]
	v_lshl_add_u64 v[10:11], s[70:71], 0, v[0:1]
	v_lshlrev_b64 v[4:5], 1, v[4:5]
	v_add_u32_e32 v148, s47, v13
	v_lshl_add_u64 v[8:9], s[72:73], 0, v[0:1]
	v_lshl_add_u64 v[130:131], v[10:11], 0, v[4:5]
	v_lshl_add_u64 v[10:11], s[70:71], 0, v[2:3]
	v_lshlrev_b64 v[6:7], 1, v[6:7]
	v_readfirstlane_b32 s47, v148
	v_add_u32_e32 v149, 0x2000, v148
	v_lshl_add_u64 v[14:15], s[72:73], 0, v[2:3]
	v_lshl_add_u64 v[128:129], v[10:11], 0, v[6:7]
	v_lshl_add_u64 v[10:11], v[8:9], 0, v[4:5]
	s_mov_b32 m0, s47
	v_readfirstlane_b32 s47, v149
	v_add_u32_e32 v150, 32, v13
	v_lshl_add_u64 v[8:9], v[14:15], 0, v[6:7]
	s_waitcnt lgkmcnt(0)
	s_barrier
	global_load_lds_dwordx4 v[10:11], off
	s_mov_b32 m0, s47
	v_readfirstlane_b32 s47, v150
	v_add_u32_e32 v151, 0x2000, v150
	global_load_lds_dwordx4 v[8:9], off
	s_mov_b32 m0, s47
	v_readfirstlane_b32 s47, v151
	global_load_lds_dwordx4 v[130:131], off
	s_mov_b32 m0, s47
	s_add_i32 s47, 32, 0x14000
	v_add_u32_e32 v152, s47, v13
	v_add_u32_e32 v153, 0x2000, v152
	v_readfirstlane_b32 s47, v152
	global_load_lds_dwordx4 v[128:129], off
	v_lshl_add_u64 v[14:15], v[10:11], 0, s[18:19]
	s_mov_b32 m0, s47
	v_readfirstlane_b32 s47, v153
	v_add_u32_e32 v154, 0x4000, v150
	global_load_lds_dwordx4 v[14:15], off
	v_lshl_add_u64 v[14:15], v[8:9], 0, s[18:19]
	s_mov_b32 m0, s47
	v_readfirstlane_b32 s47, v154
	v_add_u32_e32 v155, 0x6000, v150
	global_load_lds_dwordx4 v[14:15], off
	v_lshl_add_u64 v[14:15], v[130:131], 0, s[18:19]
	s_mov_b32 m0, s47
	v_readfirstlane_b32 s47, v155
	global_load_lds_dwordx4 v[14:15], off
	v_lshl_add_u64 v[14:15], v[128:129], 0, s[18:19]
	s_mov_b32 m0, s47
	s_andn2_b64 vcc, exec, s[12:13]
	global_load_lds_dwordx4 v[14:15], off
	s_cbranch_vccnz .LBB0_1056
	s_barrier

; #define WAIT_V(n) asm volatile("s_waitcnt vmcnt(" #n ")" ::: "memory")
; DI void gemm256(int wv0, f32x4 (&acc)[2][2][4][2], const u16* __restrict__ A, int lda, const u16* __restrict__ Bt, int ldb,
;                 int K, unsigned char* smem) {
;   u16* shm = (u16*)smem;
;   const int tid = my_tid(wv0), lane = tid & 63;
;   const int wr = wv0 >> 2, wc = wv0 & 3, fr = lane & 15, fq = lane >> 4;
;     ...
;   int sr0, sc0, sr1, sc1;
;   stage_rc(tid * 16, sr0, sc0);
;   stage_rc(tid * 16 + 8192, sr1, sc1);
;   const u16* a0 = A + (size_t)sr0 * lda + sc0;
;   const u16* a1 = A + (size_t)sr1 * lda + sc1;
;   const u16* b0 = Bt + (size_t)sr0 * ldb + sc0;
;   const u16* b1 = Bt + (size_t)sr1 * ldb + sc1;
;     ...
;   WAIT_V(0);
;   __syncthreads();
;   STAGE_B(SB(0, 0), 0, 0) STAGE_A(SA(0, 0), 0, 0)
;   STAGE_B(SB(0, 1), 1, 0) STAGE_A(SA(0, 1), 1, 0)
.LBB0_1200:
	v_mov_b32_e32 v12, v144
	s_lshr_b32 s8, s67, 2
	v_ashrrev_i32_e32 v0, 31, v12
	v_lshrrev_b32_e32 v0, 26, v0
	v_add_u32_e32 v0, v12, v0
	v_ashrrev_i32_e32 v1, 6, v0
	v_bfe_i32 v0, v12, 27, 1
	v_lshlrev_b32_e32 v13, 4, v12
	v_lshrrev_b32_e32 v0, 22, v0
	v_add_u32_e32 v0, v13, v0
	v_and_b32_e32 v0, 0xfffffc00, v0
	v_sub_u32_e32 v0, v13, v0
	v_lshrrev_b32_e32 v2, 4, v0
	v_bitop3_b32 v2, v2, v0, 32 bitop3:0x6c
	v_ashrrev_i32_e32 v0, 31, v0
	v_lshrrev_b32_e32 v0, 26, v0
	v_lshlrev_b32_e32 v3, 3, v1
	v_add_u32_e32 v0, v2, v0
	v_and_b32_e32 v3, -16, v3
	v_ashrrev_i32_e32 v4, 6, v0
	v_add_u32_e32 v0, v4, v3
	v_mul_i32_i24_e32 v3, 64, v4
	v_lshlrev_b32_e32 v1, 5, v1
	v_sub_u32_e32 v2, v2, v3
	v_and_b32_e32 v1, 32, v1
	v_ashrrev_i16_sdwa v2, v147, sext(v2) dst_sel:DWORD dst_unused:UNUSED_PAD src0_sel:DWORD src1_sel:BYTE_0
	v_add_u32_sdwa v4, v1, sext(v2) dst_sel:DWORD dst_unused:UNUSED_PAD src0_sel:DWORD src1_sel:WORD_0
	v_add_u32_e32 v1, 0x2000, v13
	v_ashrrev_i32_e32 v2, 31, v1
	v_lshrrev_b32_e32 v2, 22, v2
	v_add_u32_e32 v2, v1, v2
	v_ashrrev_i32_e32 v3, 10, v2
	s_and_b32 s48, s8, 0xffffc0
	s_lshl_b32 s8, s67, 3
	v_mul_i32_i24_e32 v2, 0x400, v3
	s_and_b32 s49, s8, 56
	v_sub_u32_e32 v1, v1, v2
	s_or_b32 s8, s48, s49
	s_bfe_u32 s69, s67, 0x30005
	v_lshrrev_b32_e32 v2, 4, v1
	s_or_b32 s8, s8, s69
	v_bitop3_b32 v1, v2, v1, 32 bitop3:0x6c
	s_lshl_b32 s8, s8, 8
	v_ashrrev_i32_e32 v5, 31, v1
	s_sub_i32 s46, 0x7f00, s8
	v_lshrrev_b32_e32 v5, 26, v5
	s_ashr_i32 s47, s46, 31
	v_add_u32_e32 v5, v1, v5
	s_bfe_u32 s68, s67, 0x20003
	s_lshl_b64 s[70:71], s[46:47], 13
	v_ashrrev_i32_e32 v6, 6, v5
	v_and_b32_e32 v5, 0xc0, v5
	s_add_u32 s70, s0, s70
	v_lshlrev_b32_e32 v2, 3, v3
	v_lshlrev_b32_e32 v3, 5, v3
	v_sub_u32_e32 v1, v1, v5
	s_addc_u32 s71, s1, s71
	s_lshl_b32 s8, s68, 21
	v_and_b32_e32 v2, -16, v2
	v_and_b32_e32 v3, 32, v3
	v_ashrrev_i16_sdwa v1, v147, sext(v1) dst_sel:DWORD dst_unused:UNUSED_PAD src0_sel:DWORD src1_sel:BYTE_0
	s_add_u32 s72, s33, s8
	v_add_u32_e32 v2, v6, v2
	v_add_u32_sdwa v6, v3, sext(v1) dst_sel:DWORD dst_unused:UNUSED_PAD src0_sel:DWORD src1_sel:WORD_0
	v_ashrrev_i32_e32 v1, 31, v0
	s_addc_u32 s73, s50, 0
	v_ashrrev_i32_e32 v5, 31, v4
	v_ashrrev_i32_e32 v3, 31, v2
	v_lshlrev_b64 v[0:1], 13, v[0:1]
	s_add_i32 s47, 32, 0x10000
	v_ashrrev_i32_e32 v7, 31, v6
	v_lshlrev_b64 v[2:3], 13, v[2:3]
	v_lshl_add_u64 v[10:11], s[70:71], 0, v[0:1]
	v_lshlrev_b64 v[4:5], 1, v[4:5]
	v_add_u32_e32 v148, s47, v13
	v_lshl_add_u64 v[8:9], s[72:73], 0, v[0:1]
	v_lshl_add_u64 v[130:131], v[10:11], 0, v[4:5]
	v_lshl_add_u64 v[10:11], s[70:71], 0, v[2:3]
	v_lshlrev_b64 v[6:7], 1, v[6:7]
	v_readfirstlane_b32 s47, v148
	v_add_u32_e32 v149, 0x2000, v148
	v_lshl_add_u64 v[14:15], s[72:73], 0, v[2:3]
	v_lshl_add_u64 v[128:129], v[10:11], 0, v[6:7]
	v_lshl_add_u64 v[10:11], v[8:9], 0, v[4:5]
	s_mov_b32 m0, s47
	v_readfirstlane_b32 s47, v149
	v_add_u32_e32 v150, 32, v13
	v_lshl_add_u64 v[8:9], v[14:15], 0, v[6:7]
	s_waitcnt lgkmcnt(0)
	s_barrier
	global_load_lds_dwordx4 v[10:11], off
	s_mov_b32 m0, s47
	v_readfirstlane_b32 s47, v150
	v_add_u32_e32 v151, 0x2000, v150
	global_load_lds_dwordx4 v[8:9], off
	s_mov_b32 m0, s47
	v_readfirstlane_b32 s47, v151
	global_load_lds_dwordx4 v[130:131], off
	s_mov_b32 m0, s47
	s_add_i32 s47, 32, 0x14000
	v_add_u32_e32 v152, s47, v13
	v_add_u32_e32 v153, 0x2000, v152
	v_readfirstlane_b32 s47, v152
	global_load_lds_dwordx4 v[128:129], off
	v_lshl_add_u64 v[14:15], v[10:11], 0, s[18:19]
	s_mov_b32 m0, s47
	v_readfirstlane_b32 s47, v153
	v_add_u32_e32 v154, 0x4000, v150
	global_load_lds_dwordx4 v[14:15], off
	v_lshl_add_u64 v[14:15], v[8:9], 0, s[18:19]
	s_mov_b32 m0, s47
	v_readfirstlane_b32 s47, v154
	v_add_u32_e32 v155, 0x6000, v150
	global_load_lds_dwordx4 v[14:15], off
	v_lshl_add_u64 v[14:15], v[130:131], 0, s[18:19]
	s_mov_b32 m0, s47
	v_readfirstlane_b32 s47, v155
	global_load_lds_dwordx4 v[14:15], off
	v_lshl_add_u64 v[14:15], v[128:129], 0, s[18:19]
	s_mov_b32 m0, s47
	s_andn2_b64 vcc, exec, s[12:13]
	global_load_lds_dwordx4 v[14:15], off
	s_cbranch_vccnz .LBB0_1202
	s_barrier
